# plus lru_chunk0: gate-weight fragments of each 64-channel block touched up front
# baseline (speedup 1.0000x reference)
; #define LAS __attribute__((address_space(3)))
; DI float softplus_f(float x) { return x > 20.f ? x : log1pf(__expf(x)); }
; template <bool OUT>
; DI void lru_sweep(LAS bf16_t* U, LAS float* SUM, const Args& a, const LayerP& P, int row0, int wv, const float* LC, f32x2* LSWc) {
;     ...
;         bf16x8 af[2];
; #pragma unroll
;         for (int ks = 0; ks < 2; ++ks) af[ks] = *(const LAS bf16x8*)(U + (l0 + r) * PU + g * 64 + ks * 32 + q * 8);
; #pragma unroll
;         for (int ni = 0; ni < 4; ++ni) { f32x4 aa1 = (f32x4){0.f, 0.f, 0.f, 0.f}, ax1 = aa1;
; #pragma unroll
;             for (int ks = 0; ks < 2; ++ks) { const bf16x8 wa = *(const bf16x8*)(LWT + ((size_t)(g * 64 + ni * 16 + r)) * 64 + ks * 32 + q * 8), wx = *(const bf16x8*)(LWT + ((size_t)((4 + g) * 64 + ni * 16 + r)) * 64 + ks * 32 + q * 8);
;                 aa1 = __builtin_amdgcn_mfma_f32_16x16x32_bf16(af[ks], wa, aa1, 0, 0, 0); ax1 = __builtin_amdgcn_mfma_f32_16x16x32_bf16(af[ks], wx, ax1, 0, 0, 0); }
;             const int ch = g * 64 + ni * 16 + r; const float ba = P.lru_ba[ch], bx = P.lru_bx[ch], c8 = -8.0f * softplus_f(-P.lru_ap[ch]);
.LBB0_1034:
	s_waitcnt lgkmcnt(4)
	v_mbcnt_lo_u32_b32 v0, -1, 0
	v_mbcnt_hi_u32_b32 v0, -1, v0
	s_mov_b32 s2, s77
	v_and_b32_e32 v40, 15, v0
	v_bfe_u32 v36, v0, 4, 2
	v_lshl_add_u32 v24, v40, 6, s34
	v_mov_b32_e32 v25, v1
	v_lshlrev_b32_e32 v0, 4, v36
	v_lshl_add_u64 v[10:11], v[24:25], 1, s[48:49]
	v_lshl_add_u64 v[26:27], v[10:11], 0, v[0:1]
	global_load_dwordx4 v[116:119], v[26:27], off
	global_load_dwordx4 v[116:119], v[26:27], off offset:64
	global_load_dwordx4 v[116:119], v[26:27], off offset:2048
	global_load_dwordx4 v[116:119], v[26:27], off offset:2112
	s_mov_b64 s[42:43], 0x1000
	v_lshl_add_u64 v[110:111], v[26:27], 0, s[42:43]
	global_load_dwordx4 v[116:119], v[110:111], off
	global_load_dwordx4 v[116:119], v[110:111], off offset:64
	global_load_dwordx4 v[116:119], v[110:111], off offset:2048
	global_load_dwordx4 v[116:119], v[110:111], off offset:2112
	s_mov_b64 s[42:43], 0x8000
	v_lshl_add_u64 v[112:113], v[26:27], 0, s[42:43]
	global_load_dwordx4 v[116:119], v[112:113], off
	global_load_dwordx4 v[116:119], v[112:113], off offset:64
	global_load_dwordx4 v[116:119], v[112:113], off offset:2048
	global_load_dwordx4 v[116:119], v[112:113], off offset:2112
	s_mov_b64 s[42:43], 0x9000
	v_lshl_add_u64 v[114:115], v[26:27], 0, s[42:43]
	global_load_dwordx4 v[116:119], v[114:115], off
	global_load_dwordx4 v[116:119], v[114:115], off offset:64
	global_load_dwordx4 v[116:119], v[114:115], off offset:2048
	global_load_dwordx4 v[116:119], v[114:115], off offset:2112
	s_mov_b32 s2, 0x8000
	s_waitcnt lgkmcnt(2)
	v_mul_u32_u24_e32 v2, 0x210, v40
	v_add_co_u32_e32 v14, vcc, s2, v26
	v_add3_u32 v2, v2, v0, s35
	s_nop 0
	v_addc_co_u32_e32 v15, vcc, 0, v27, vcc
	s_waitcnt lgkmcnt(0)
	ds_read_b128 v[6:9], v2
	ds_read_b128 v[2:5], v2 offset:64
	global_load_dwordx4 v[10:13], v[26:27], off
	v_lshl_add_u64 v[22:23], v[26:27], 0, s[52:53]
	global_load_dwordx4 v[14:17], v[14:15], off
	v_add_u32_e32 v32, s40, v40
	v_mov_b32_e32 v0, v32
	s_waitcnt vmcnt(1) lgkmcnt(1)
	v_mfma_f32_16x16x32_bf16 v[10:13], v[6:9], v[10:13], 0
	s_waitcnt vmcnt(0)
	v_mfma_f32_16x16x32_bf16 v[18:21], v[6:9], v[14:17], 0
	global_load_dwordx4 v[14:17], v[26:27], off offset:64
	global_load_dwordx4 v[28:31], v[22:23], off offset:64
	v_lshlrev_b64 v[22:23], 2, v[0:1]
	s_waitcnt vmcnt(1) lgkmcnt(0)
	v_mfma_f32_16x16x32_bf16 v[14:17], v[2:5], v[14:17], v[10:13]
	s_waitcnt vmcnt(0)
	v_mfma_f32_16x16x32_bf16 v[10:13], v[2:5], v[28:31], v[18:21]
	s_nop 2
	v_lshl_add_u64 v[18:19], s[26:27], 0, v[22:23]
	v_lshl_add_u64 v[20:21], s[36:37], 0, v[22:23]
	v_lshl_add_u64 v[22:23], s[38:39], 0, v[22:23]
	global_load_dword v28, v[22:23], off
	global_load_dword v30, v[18:19], off
	global_load_dword v25, v[20:21], off
	s_waitcnt vmcnt(2)
	v_xor_b32_e32 v29, 0x80000000, v28
	v_cmp_ngt_f32_e32 vcc, s78, v28
	s_and_saveexec_b64 s[2:3], vcc
	s_cbranch_execz .LBB0_1036
; DI float softplus_f(float x) { return x > 20.f ? x : log1pf(__expf(x)); }
; template <bool OUT>
; DI void lru_sweep(LAS bf16_t* U, LAS float* SUM, const Args& a, const LayerP& P, int row0, int wv, const float* LC, f32x2* LSWc) {
;     ...
;             const int ch = g * 64 + ni * 16 + r; const float ba = P.lru_ba[ch], bx = P.lru_bx[ch], c8 = -8.0f * softplus_f(-P.lru_ap[ch]);
	v_mul_f32_e32 v28, 0xbfb8aa3b, v28
	v_exp_f32_e32 v31, v28
	s_nop 0
	v_add_f32_e32 v32, 1.0, v31
	v_frexp_mant_f32_e32 v34, v32
	v_cvt_f64_f32_e32 v[28:29], v32
	v_frexp_exp_i32_f64_e32 v28, v[28:29]
	v_cmp_gt_f32_e32 vcc, s75, v34
	v_add_f32_e32 v33, -1.0, v32
	v_sub_f32_e32 v35, v33, v32
	v_subbrev_co_u32_e32 v37, vcc, 0, v28, vcc
	v_sub_u32_e32 v28, 0, v37
	v_sub_f32_e32 v33, v31, v33
	v_add_f32_e32 v35, 1.0, v35
	v_ldexp_f32 v29, v32, v28
	v_add_f32_e32 v33, v33, v35
	v_add_f32_e32 v32, -1.0, v29
	v_add_f32_e32 v34, 1.0, v29
	v_ldexp_f32 v28, v33, v28
	v_add_f32_e32 v33, 1.0, v32
	v_add_f32_e32 v35, -1.0, v34
	v_sub_f32_e32 v33, v29, v33
	v_sub_f32_e32 v29, v29, v35
	v_add_f32_e32 v33, v28, v33
	v_add_f32_e32 v28, v28, v29
	v_add_f32_e32 v41, v34, v28
	v_rcp_f32_e32 v43, v41
	v_sub_f32_e32 v29, v41, v34
	v_sub_f32_e32 v42, v28, v29
	v_add_f32_e32 v29, v32, v33
	v_mul_f32_e32 v45, v29, v43
	v_sub_f32_e32 v28, v29, v32
	v_mul_f32_e32 v32, v41, v45
	v_fma_f32 v34, v45, v41, -v32
	v_fmac_f32_e32 v34, v45, v42
	v_sub_f32_e32 v44, v33, v28
	v_add_f32_e32 v28, v32, v34
	v_sub_f32_e32 v33, v29, v28
	v_pk_add_f32 v[38:39], v[28:29], v[32:33] neg_lo:[0,1] neg_hi:[0,1]
	v_mov_b32_e32 v35, v28
	v_pk_add_f32 v[28:29], v[38:39], v[34:35] neg_lo:[0,1] neg_hi:[0,1]
	v_cmp_neq_f32_e32 vcc, s84, v31
	v_add_f32_e32 v29, v44, v29
	v_add_f32_e32 v28, v28, v29
	v_add_f32_e32 v29, v33, v28
	v_mul_f32_e32 v44, v43, v29
	v_mul_f32_e32 v32, v41, v44
	v_fma_f32 v34, v44, v41, -v32
	v_fmac_f32_e32 v34, v44, v42
	v_sub_f32_e32 v33, v33, v29
	v_add_f32_e32 v41, v28, v33
	v_add_f32_e32 v28, v32, v34
	v_sub_f32_e32 v33, v29, v28
	v_pk_add_f32 v[38:39], v[28:29], v[32:33] neg_lo:[0,1] neg_hi:[0,1]
	v_mov_b32_e32 v35, v28
	v_pk_add_f32 v[28:29], v[38:39], v[34:35] neg_lo:[0,1] neg_hi:[0,1]
	s_nop 0
	v_add_f32_e32 v29, v41, v29
	v_add_f32_e32 v28, v28, v29
	v_add_f32_e32 v29, v45, v44
	v_add_f32_e32 v28, v33, v28
	v_sub_f32_e32 v32, v29, v45
	v_mul_f32_e32 v28, v43, v28
	v_sub_f32_e32 v32, v44, v32
	v_add_f32_e32 v32, v32, v28
	v_add_f32_e32 v34, v29, v32
	v_mul_f32_e32 v35, v34, v34
	v_fmamk_f32 v28, v35, 0x3e9b6dac, v203
	v_fmaak_f32 v189, v35, v28, 0x3f2aaada
	v_cvt_f32_i32_e32 v28, v37
	v_sub_f32_e32 v29, v34, v29
	v_sub_f32_e32 v29, v32, v29
	v_ldexp_f32 v37, v29, 1
	v_mul_f32_e32 v29, v34, v35
	v_ldexp_f32 v33, v34, 1
	v_pk_mul_f32 v[34:35], v[28:29], v[188:189]
	s_nop 0
	v_fma_f32 v32, v28, s31, -v34
	v_fmac_f32_e32 v32, 0xb102e308, v28
	v_pk_add_f32 v[28:29], v[34:35], v[32:33]
	v_mov_b32_e32 v38, v34
	v_sub_f32_e32 v33, v29, v33
	v_sub_f32_e32 v33, v35, v33
	v_add_f32_e32 v39, v37, v33
	v_pk_add_f32 v[34:35], v[28:29], v[34:35] neg_lo:[0,1] neg_hi:[0,1]
	v_pk_add_f32 v[42:43], v[28:29], v[38:39]
	v_mov_b32_e32 v33, v28
	v_mov_b32_e32 v35, v43
	v_pk_add_f32 v[44:45], v[32:33], v[34:35] neg_lo:[0,1] neg_hi:[0,1]
	v_pk_add_f32 v[32:33], v[32:33], v[34:35]
	v_mov_b32_e32 v38, v39
	v_pk_add_f32 v[34:35], v[32:33], v[28:29] op_sel:[1,0] op_sel_hi:[0,1] neg_lo:[0,1] neg_hi:[0,1]
	v_pk_add_f32 v[46:47], v[42:43], v[34:35] op_sel_hi:[1,0] neg_lo:[0,1] neg_hi:[0,1]
	v_mov_b32_e32 v42, v43
	v_mov_b32_e32 v43, v33
	v_pk_mov_b32 v[34:35], v[28:29], v[34:35] op_sel:[1,0]
	v_mov_b32_e32 v39, v28
	v_pk_add_f32 v[34:35], v[42:43], v[34:35] neg_lo:[0,1] neg_hi:[0,1]
	v_mov_b32_e32 v46, v44
	v_pk_add_f32 v[28:29], v[38:39], v[34:35] neg_lo:[0,1] neg_hi:[0,1]
	v_mov_b32_e32 v45, v33
	v_pk_add_f32 v[34:35], v[46:47], v[28:29]
	s_nop 0
	v_pk_add_f32 v[38:39], v[34:35], v[34:35] op_sel:[0,1] op_sel_hi:[1,0]
	s_nop 0
	v_pk_add_f32 v[32:33], v[32:33], v[38:39] op_sel:[1,0] op_sel_hi:[0,1]
	v_mov_b32_e32 v35, v32
	v_pk_add_f32 v[42:43], v[34:35], v[44:45] neg_lo:[0,1] neg_hi:[0,1]
	v_mov_b32_e32 v29, v38
	v_sub_f32_e32 v33, v34, v42
	v_pk_add_f32 v[28:29], v[28:29], v[42:43] neg_lo:[0,1] neg_hi:[0,1]
	v_sub_f32_e32 v33, v44, v33
	v_add_f32_e32 v28, v28, v33
	v_add_f32_e32 v28, v28, v29
	v_add_f32_e32 v28, v32, v28
	v_cndmask_b32_e32 v28, v206, v28, vcc
	v_cmp_ngt_f32_e32 vcc, -1.0, v31
	s_nop 1
	v_cndmask_b32_e32 v28, v207, v28, vcc
	v_cmp_neq_f32_e32 vcc, -1.0, v31
	s_nop 1
	v_cndmask_b32_e32 v28, v208, v28, vcc
	v_cmp_lt_f32_e64 vcc, |v31|, s85
	s_nop 1
	v_cndmask_b32_e32 v29, v28, v31, vcc
